# scan phase: nt cache policy on the once-read record/U loads (LDS-DMA + U tiles)
# speedup vs baseline: 1.0133x; 1.0133x over previous
; __device__ __forceinline__ void gdn_scan_phase(const Frame& F0, const Args& a0, int nblk, bool last) {
;     const Frame F = relaunder(F0); const Args a = relaunder_args(a0);
;     const int chain = F.bx; if (chain >= nblk) return;
; __global__ void __launch_bounds__(NTHREADS, 2) fwd(Args args) {
;     ...
;         if (IN(GP(l, 3))) for (int rep = 0; rep < REP_MIX; ++rep) {
;             for (int r2 = 0; r2 < REP_SCAN; ++r2) gdn_scan_phase(F, args, 64, last);
.LBB0_564:
	s_cmp_eq_u32 s24, 3
	s_cselect_b64 s[76:77], -1, 0
	s_cmp_lg_u32 s24, 3
	s_cselect_b64 s[80:81], -1, 0
	s_cmp_le_i32 s64, s18
	s_cselect_b64 s[2:3], -1, 0
	s_and_b64 s[34:35], s[2:3], s[0:1]
	s_andn2_b64 vcc, exec, s[34:35]
	s_cbranch_vccnz .LBB0_687
	s_mov_b32 s0, s93
	s_mov_b32 s7, s94
	s_mov_b32 s6, s95
	s_mov_b32 s1, s92
	v_readlane_b32 s48, v221, 0
	s_waitcnt vmcnt(0)
	v_mbcnt_lo_u32_b32 v0, -1, 0
	v_mbcnt_hi_u32_b32 v0, -1, v0
	v_readlane_b32 s49, v221, 1
	s_mov_b64 s[0:1], s[48:49]
	v_readlane_b32 s50, v221, 2
	v_readlane_b32 s51, v221, 3
	s_mov_b64 s[0:1], s[50:51]
	v_readlane_b32 s52, v221, 4
	v_readlane_b32 s53, v221, 5
	s_mov_b64 s[0:1], s[52:53]
	v_readlane_b32 s54, v221, 6
	v_readlane_b32 s55, v221, 7
	s_mov_b64 s[0:1], s[54:55]
	v_readlane_b32 s56, v221, 8
	v_readlane_b32 s57, v221, 9
	s_mov_b64 s[0:1], s[56:57]
	v_readlane_b32 s58, v221, 10
	v_readlane_b32 s59, v221, 11
	s_mov_b64 s[0:1], s[58:59]
	v_readlane_b32 s60, v221, 12
	v_readlane_b32 s61, v221, 13
	s_mov_b64 s[0:1], s[60:61]
	v_readlane_b32 s62, v221, 14
	v_readlane_b32 s63, v221, 15
	s_mov_b64 s[0:1], s[62:63]
	v_readlane_b32 s48, v221, 16
	v_readlane_b32 s49, v221, 17
	s_mov_b64 s[0:1], s[48:49]
	v_readlane_b32 s50, v221, 18
	v_readlane_b32 s51, v221, 19
	s_mov_b64 s[0:1], s[50:51]
	v_readlane_b32 s52, v221, 20
	v_readlane_b32 s53, v221, 21
	s_mov_b64 s[0:1], s[52:53]
	v_readlane_b32 s54, v221, 22
	v_readlane_b32 s55, v221, 23
	s_mov_b64 s[0:1], s[54:55]
	v_readlane_b32 s56, v221, 24
	v_readlane_b32 s57, v221, 25
	s_mov_b64 s[0:1], s[56:57]
	v_readlane_b32 s58, v221, 26
	v_readlane_b32 s59, v221, 27
	s_mov_b64 s[0:1], s[58:59]
	v_readlane_b32 s60, v221, 28
	v_readlane_b32 s61, v221, 29
	s_mov_b64 s[0:1], s[60:61]
	v_readlane_b32 s62, v221, 30
	v_readlane_b32 s63, v221, 31
	s_mov_b64 s[0:1], s[62:63]
	s_mov_b64 s[0:1], s[40:41]
	s_mov_b64 s[0:1], s[42:43]
	s_mov_b64 s[0:1], s[44:45]
	s_mov_b64 s[0:1], s[46:47]
	s_cmp_gt_i32 s7, 63
	s_cbranch_scc1 .LBB0_578
; #define LAS __attribute__((address_space(3)))
; #define VM_WAIT() asm volatile("s_waitcnt vmcnt(0)" ::: "memory")
; #define GD_GLDS(cidx, buf) do { const unsigned char* src_ = REC + (size_t)(cidx) * GD_REC + lane * 16; \
;         _Pragma("unroll") for (int k_ = 0; k_ < 7; ++k_) __builtin_amdgcn_global_load_lds((const unsigned*)(src_ + (n + 8 * k_) * 1024), (LAS unsigned*)(lds + (buf) * GD_REC + (n + 8 * k_) * 1024), 16, 0, 0); } while (0)
; __device__ __forceinline__ void gdn_scan_phase(const Frame& F0, const Args& a0, int nblk, bool last) {
;     ...
;     const int d = chain & 1, h = (chain >> 1) & 7, b = chain >> 4;
;     const unsigned char* REC = a.ws + WS_GREC + (size_t)chain * 36 * GD_REC; const float* UB = (const float*)(a.ws + WS_GU) + (size_t)chain * 36 * 8192; const float* GLB = (const float*)(a.ws + WS_GL) + (size_t)chain * 36;
;     bf16* GOb = (bf16*)(a.ws + WS_GO2) + (size_t)d * M * 1024;
;     LAS unsigned char* lds = F.lds + RING_OFF;
;     LAS unsigned char* ost = lds + 2 * GD_REC;
;     const int lane = F.lane, n = F.wave, cc = lane & 15, g = lane >> 4;
;     f32x4 S[8];
; #pragma unroll
;     for (int t = 0; t < 8; ++t) S[t] = (f32x4){0.f, 0.f, 0.f, 0.f};
;     ...
;     f32x4 un[4]; float gln;
;     { const int c0 = GD_CHUNK(0); GD_GLDS(c0, 0);
; #pragma unroll
;       for (int mt = 0; mt < 4; ++mt) un[mt] = *(const f32x4*)(UB + (size_t)c0 * 8192 + ((mt * 8 + n) * 64 + lane) * 4);
;       gln = GLB[c0]; }
;     VM_WAIT(); __syncthreads();
;     int cprev = -1;
	s_and_b64 s[2:3], s[76:77], exec
	s_cselect_b32 s22, 4, 0
	s_and_b32 s10, s7, 1
	s_bfe_i32 s11, s7, 0x10000
	s_lshr_b32 s18, s7, 4
	s_mul_i32 s5, s7, 0x120000
	s_mul_hi_i32 s4, s7, 0x120000
	s_add_u32 s5, s0, s5
	s_addc_u32 s4, s1, s4
	s_add_u32 s23, s5, 0x46e00000
	s_addc_u32 s24, s4, 0
	s_mul_i32 s8, s10, 0x1200000
	s_add_u32 s8, s0, s8
	s_mul_i32 s3, s7, 0x1f8000
	s_addc_u32 s9, s1, 0
	s_mul_hi_i32 s2, s7, 0x1f8000
	s_add_u32 s3, s0, s3
	s_addc_u32 s12, s1, s2
	s_add_u32 s2, s3, 0.5
	s_mul_i32 s5, s7, 0x90
	s_addc_u32 s3, s12, 0
	s_mul_hi_i32 s4, s7, 0x90
	s_add_u32 s0, s0, s5
	s_addc_u32 s1, s1, s4
	s_add_u32 s0, s0, 0x4b600000
	s_addc_u32 s1, s1, 0
	s_cmp_eq_u32 s10, 0
	s_cselect_b64 s[4:5], -1, 0
	s_cmp_eq_u32 s10, 1
	v_and_b32_e32 v8, 1, v0
	s_cselect_b64 s[12:13], -1, 0
	s_and_b32 s14, s11, 3
	v_ashrrev_i32_e32 v2, 2, v0
	v_lshlrev_b32_e32 v3, 1, v8
	s_mul_i32 s10, s14, 0xe000
	v_and_or_b32 v9, v2, -4, v3
	s_add_u32 s10, s2, s10
	v_lshlrev_b32_e32 v2, 4, v0
	s_addc_u32 s11, s3, 0
	v_ashrrev_i32_e32 v3, 31, v2
	s_lshl_b32 s30, s6, 10
	v_lshl_add_u64 v[4:5], s[10:11], 0, v[2:3]
	s_ashr_i32 s31, s30, 31
	s_add_i32 s25, s30, 0
	s_add_i32 s68, s30, 0x2000
	v_lshl_add_u64 v[6:7], v[4:5], 0, s[30:31]
	s_mov_b32 m0, s25
	s_ashr_i32 s69, s68, 31
	s_add_i32 s70, s30, 0x4000
	global_load_lds_dwordx4 v[6:7], off nt
	v_lshl_add_u64 v[6:7], v[4:5], 0, s[68:69]
	s_add_i32 m0, s25, 0x2000
	s_ashr_i32 s71, s70, 31
	s_add_i32 s74, s30, 0x6000
	global_load_lds_dwordx4 v[6:7], off nt
	v_lshl_add_u64 v[6:7], v[4:5], 0, s[70:71]
	s_add_i32 m0, s25, 0x4000
	s_ashr_i32 s75, s74, 31
	s_add_i32 s78, s30, 0x8000
	global_load_lds_dwordx4 v[6:7], off nt
	v_lshl_add_u64 v[6:7], v[4:5], 0, s[74:75]
	s_add_i32 m0, s25, 0x6000
	s_ashr_i32 s79, s78, 31
	s_add_i32 s82, s30, 0xa000
	global_load_lds_dwordx4 v[6:7], off nt
	v_lshl_add_u64 v[6:7], v[4:5], 0, s[78:79]
	s_add_i32 m0, s25, 0x8000
	s_ashr_i32 s83, s82, 31
	v_lshl_add_u32 v1, s6, 6, v0
	global_load_lds_dwordx4 v[6:7], off nt
	v_lshl_add_u64 v[6:7], v[4:5], 0, s[82:83]
	s_add_i32 m0, s25, 0xa000
	s_add_i32 s88, s30, 0xc000
	global_load_lds_dwordx4 v[6:7], off nt
	s_ashr_i32 s89, s88, 31
	s_add_i32 m0, s25, 0xc000
	s_lshl_b32 s10, s14, 15
	v_lshlrev_b32_e32 v70, 2, v1
	s_add_u32 s10, s23, s10
	v_add_u32_e32 v72, 0x800, v70
	v_lshl_add_u64 v[4:5], v[4:5], 0, s[88:89]
	s_addc_u32 s11, s24, 0
	v_ashrrev_i32_e32 v71, 31, v70
	v_ashrrev_i32_e32 v73, 31, v72
	v_add_u32_e32 v74, 0x1000, v70
	v_add_u32_e32 v76, 0x1800, v70
	global_load_lds_dwordx4 v[4:5], off nt
	v_lshl_add_u64 v[4:5], v[70:71], 2, s[10:11]
	v_lshl_add_u64 v[6:7], v[72:73], 2, s[10:11]
	v_ashrrev_i32_e32 v75, 31, v74
	v_ashrrev_i32_e32 v77, 31, v76
	global_load_dwordx4 v[60:63], v[4:5], off nt
	global_load_dwordx4 v[56:59], v[6:7], off nt
	v_lshl_add_u64 v[4:5], v[74:75], 2, s[10:11]
	v_lshl_add_u64 v[6:7], v[76:77], 2, s[10:11]
	s_lshl_b32 s10, s14, 2
	global_load_dwordx4 v[52:55], v[4:5], off nt
	global_load_dwordx4 v[48:51], v[6:7], off nt
	v_mov_b32_e32 v4, s10
	global_load_dword v80, v4, s[0:1]
	v_lshl_add_u64 v[78:79], s[2:3], 0, v[2:3]
	v_and_b32_e32 v160, 0xf0, v2
	s_movk_i32 s2, 0xc0
	v_bitop3_b32 v67, v1, v160, s2 bitop3:0x6c
	s_add_i32 s2, 0, 0x1c000
	v_add_u32_e32 v102, s2, v67
	s_lshl_b32 s2, s7, 7
	s_and_b32 s2, s2, 0x700
	s_add_u32 s2, s8, s2
	s_addc_u32 s3, s9, 0
	v_add_u32_e32 v101, 0, v2
	v_lshl_add_u64 v[2:3], s[2:3], 0, v[160:161]
	s_mov_b64 s[2:3], 0x4b800000
	v_lshl_add_u64 v[64:65], v[2:3], 0, s[2:3]
	v_bfe_u32 v2, v0, 3, 1
	v_lshlrev_b32_e32 v0, 1, v0
	v_sub_u32_e32 v10, 63, v9
	v_and_b32_e32 v84, 12, v0
	v_add_u32_e32 v0, 0x200, v1
	v_lshl_or_b32 v2, s6, 1, v2
	v_ashrrev_i32_e32 v69, 4, v0
	v_cndmask_b32_e64 v0, v10, v9, s[4:5]
	v_lshlrev_b32_e32 v97, 8, v0
	v_bitop3_b32 v0, v0, v2, 12 bitop3:0x6c
	v_lshlrev_b32_e32 v98, 4, v0
	v_or_b32_e32 v0, 1, v9
	v_ashrrev_i32_e32 v82, 4, v1
	v_sub_u32_e32 v1, 63, v0
	v_cndmask_b32_e64 v0, v1, v0, s[4:5]
	v_lshlrev_b32_e32 v99, 8, v0
	v_bitop3_b32 v0, v0, v2, 12 bitop3:0x6c
	v_lshlrev_b32_e32 v100, 4, v0
	v_add_u32_e32 v0, 16, v9
	v_sub_u32_e32 v1, 47, v9
	v_cndmask_b32_e64 v0, v1, v0, s[4:5]
	v_lshlrev_b32_e32 v93, 8, v0
	v_bitop3_b32 v0, v0, v2, 12 bitop3:0x6c
	v_lshlrev_b32_e32 v94, 4, v0
	v_add_u32_e32 v0, 17, v9
	v_sub_u32_e32 v1, 46, v9
	v_cndmask_b32_e64 v0, v1, v0, s[4:5]
	v_lshlrev_b32_e32 v95, 8, v0
	v_bitop3_b32 v0, v0, v2, 12 bitop3:0x6c
	v_lshlrev_b32_e32 v96, 4, v0
	v_add_u32_e32 v0, 32, v9
	v_sub_u32_e32 v1, 31, v9
	v_cndmask_b32_e64 v0, v1, v0, s[4:5]
	v_lshlrev_b32_e32 v89, 8, v0
	v_bitop3_b32 v0, v0, v2, 12 bitop3:0x6c
	v_lshlrev_b32_e32 v90, 4, v0
	v_add_u32_e32 v0, 33, v9
	v_sub_u32_e32 v1, 30, v9
	v_cndmask_b32_e64 v0, v1, v0, s[4:5]
	v_lshlrev_b32_e32 v91, 8, v0
	v_bitop3_b32 v0, v0, v2, 12 bitop3:0x6c
	v_lshlrev_b32_e32 v92, 4, v0
	v_add_u32_e32 v0, 48, v9
	v_sub_u32_e32 v1, 15, v9
	v_cndmask_b32_e64 v0, v1, v0, s[4:5]
	v_lshlrev_b32_e32 v85, 8, v0
	v_bitop3_b32 v0, v0, v2, 12 bitop3:0x6c
	v_lshlrev_b32_e32 v86, 4, v0
	v_add_u32_e32 v0, 49, v9
	v_sub_u32_e32 v1, 14, v9
	v_cndmask_b32_e64 v0, v1, v0, s[4:5]
	s_waitcnt vmcnt(0)
	v_lshlrev_b32_e32 v87, 8, v0
	v_bitop3_b32 v0, v0, v2, 12 bitop3:0x6c
	v_lshlrev_b32_e32 v88, 4, v0
	v_cmp_eq_u32_e64 s[2:3], 0, v8
	v_mov_b32_e32 v0, 0
	s_mov_b32 s19, 0
	s_mulk_i32 s18, 0x900
	v_lshlrev_b32_e32 v83, 8, v82
	v_lshlrev_b32_e32 v81, 8, v69
	v_cndmask_b32_e64 v68, 0, 2, s[2:3]
	v_cndmask_b32_e64 v66, 1, 3, s[2:3]
	s_mov_b32 s27, -1
	s_mov_b32 s26, 38
	s_mov_b32 s8, 0
	v_mov_b32_e32 v1, v0
	v_mov_b32_e32 v2, v0
	v_mov_b32_e32 v3, v0
	v_mov_b32_e32 v4, v0
	v_mov_b32_e32 v5, v0
	v_mov_b32_e32 v6, v0
	v_mov_b32_e32 v7, v0
	v_mov_b32_e32 v8, v0
	v_mov_b32_e32 v9, v0
	v_mov_b32_e32 v10, v0
	v_mov_b32_e32 v11, v0
	v_mov_b32_e32 v12, v0
	v_mov_b32_e32 v13, v0
	v_mov_b32_e32 v14, v0
	v_mov_b32_e32 v15, v0
	v_mov_b32_e32 v16, v0
	v_mov_b32_e32 v17, v0
	v_mov_b32_e32 v18, v0
	v_mov_b32_e32 v19, v0
	v_mov_b32_e32 v20, v0
	v_mov_b32_e32 v21, v0
	v_mov_b32_e32 v22, v0
	v_mov_b32_e32 v23, v0
	v_mov_b32_e32 v24, v0
	v_mov_b32_e32 v25, v0
	v_mov_b32_e32 v26, v0
	v_mov_b32_e32 v27, v0
	v_mov_b32_e32 v28, v0
	v_mov_b32_e32 v29, v0
	v_mov_b32_e32 v30, v0
	v_mov_b32_e32 v31, v0
	s_waitcnt vmcnt(0) lgkmcnt(0)
	s_barrier
	s_cmp_lt_i32 s27, s22
	s_cbranch_scc1 .LBB0_569
	s_branch .LBB0_568

; #define LAS __attribute__((address_space(3)))
; #define GD_GLDS(cidx, buf) do { const unsigned char* src_ = REC + (size_t)(cidx) * GD_REC + lane * 16; \
;         _Pragma("unroll") for (int k_ = 0; k_ < 7; ++k_) __builtin_amdgcn_global_load_lds((const unsigned*)(src_ + (n + 8 * k_) * 1024), (LAS unsigned*)(lds + (buf) * GD_REC + (n + 8 * k_) * 1024), 16, 0, 0); } while (0)
; #define GD_STORE_ROWS(cidx, buf) do { _Pragma("unroll") for (int i_ = 0; i_ < 2; ++i_) { const int id_ = F.tid + 512 * i_, row_ = id_ >> 4, ch_ = id_ & 15; \
;         const v4u v_ = *(const LAS v4u*)(ost + (buf) * 16384 + row_ * 256 + ((ch_ ^ (((row_ >> 2) & 3) << 2)) * 16)); \
;         *(v4u*)(GOb + (size_t)(b * TT + 64 * (cidx) + row_) * 1024 + h * 128 + ch_ * 8) = v_; } } while (0)
; #define GD_LOAD8(dst, f0) do { _Pragma("unroll") for (int i_ = 0; i_ < 8; ++i_) dst[i_] = GD_FRAG((f0) + i_); } while (0)
; __device__ __forceinline__ void gdn_scan_phase(const Frame& F0, const Args& a0, int nblk, bool last) {
;     ...
;     for (int s = 0; s < 36; ++s) {
;         const int c = GD_CHUNK(s);
;         f32x4 V[4]; const float gl = gln;
; #pragma unroll
;         for (int mt = 0; mt < 4; ++mt) V[mt] = un[mt];
;         if (cprev >= 0 && !(last && cprev < 4)) GD_STORE_ROWS(cprev, (s + 1) & 1);
;         if (s + 1 < 36) { const int cn = GD_CHUNK(s + 1);
; #pragma unroll
;             for (int mt = 0; mt < 4; ++mt) un[mt] = *(const f32x4*)(UB + (size_t)cn * 8192 + ((mt * 8 + n) * 64 + lane) * 4);
;             gln = GLB[cn];
;             GD_GLDS(cn, (s + 1) & 1); }
;         const LAS unsigned char* Bf = lds + (s & 1) * GD_REC + lane * 16;
;     ...
;         bf16x8 fA[8], fB[8], fC[8];
;     ...
;         GD_LOAD8(fA, 0); GD_LOAD8(fB, 8);
;         bf16x8 Sf[4];
; #pragma unroll
;         for (int kb = 0; kb < 4; ++kb) Sf[kb] = pack8(S[2 * kb], S[2 * kb + 1]);
;         f32x4 O[4];
; #pragma unroll
;         for (int mt = 0; mt < 4; ++mt) O[mt] = (f32x4){0.f, 0.f, 0.f, 0.f};
;         GD_PIN();
; #pragma unroll
;         for (int i = 0; i < 8; ++i) V[i >> 2] = __builtin_amdgcn_mfma_f32_16x16x32_bf16(fA[i], Sf[i & 3], V[i >> 2], 0, 0, 0);
;         GD_PIN(); GD_LOAD8(fC, 16); GD_PIN();
; #pragma unroll
;         for (int i = 0; i < 8; ++i) V[2 + (i >> 2)] = __builtin_amdgcn_mfma_f32_16x16x32_bf16(fB[i], Sf[i & 3], V[2 + (i >> 2)], 0, 0, 0);
;         GD_PIN(); GD_LOAD8(fA, 24); GD_PIN();
.LBB0_572:
	s_cmp_gt_u32 s8, 3
	s_cselect_b32 s7, 39, 3
	s_add_i32 s7, s7, s26
	s_sub_i32 s7, s7, 38
	s_and_b64 s[10:11], s[4:5], exec
	s_cselect_b32 s27, s8, s7
	s_ashr_i32 s7, s6, 31
	s_lshl_b64 s[10:11], s[6:7], 15
	s_add_u32 s10, s23, s10
	s_addc_u32 s11, s24, s11
	v_lshl_add_u64 v[32:33], v[70:71], 2, s[10:11]
	v_lshl_add_u64 v[34:35], v[72:73], 2, s[10:11]
	global_load_dwordx4 v[44:47], v[32:33], off nt
	global_load_dwordx4 v[40:43], v[34:35], off nt
	v_lshl_add_u64 v[32:33], v[74:75], 2, s[10:11]
	v_lshl_add_u64 v[34:35], v[76:77], 2, s[10:11]
	s_lshl_b64 s[10:11], s[6:7], 2
	s_add_u32 s10, s0, s10
	s_addc_u32 s11, s1, s11
	v_mad_i64_i32 v[104:105], s[6:7], s6, v193, v[78:79]
	s_bitcmp1_b32 s29, 0
	s_cselect_b32 s6, 0xe000, 0
	s_add_i32 s6, s25, s6
	v_lshl_add_u64 v[106:107], v[104:105], 0, s[30:31]
	s_mov_b32 m0, s6
	global_load_dwordx4 v[36:39], v[32:33], off nt
	s_nop 0
	global_load_dwordx4 v[32:35], v[34:35], off nt
	v_cvt_pk_bf16_f32 v170, v28, v29
	global_load_lds_dwordx4 v[106:107], off nt
	v_lshl_add_u64 v[106:107], v[104:105], 0, s[68:69]
	s_add_i32 m0, s6, 0x2000
	global_load_dword v103, v161, s[10:11]
	v_cvt_pk_bf16_f32 v171, v30, v31
	global_load_lds_dwordx4 v[106:107], off nt
	v_lshl_add_u64 v[106:107], v[104:105], 0, s[70:71]
	s_add_i32 m0, s6, 0x4000
	v_cvt_pk_bf16_f32 v172, v24, v25
	global_load_lds_dwordx4 v[106:107], off nt
	v_lshl_add_u64 v[106:107], v[104:105], 0, s[74:75]
	s_add_i32 m0, s6, 0x6000
	v_cvt_pk_bf16_f32 v173, v26, v27
	global_load_lds_dwordx4 v[106:107], off nt
	v_lshl_add_u64 v[106:107], v[104:105], 0, s[78:79]
	s_add_i32 m0, s6, 0x8000
	v_cvt_pk_bf16_f32 v174, v20, v21
	global_load_lds_dwordx4 v[106:107], off nt
	v_lshl_add_u64 v[106:107], v[104:105], 0, s[82:83]
	s_add_i32 m0, s6, 0xa000
	v_lshl_add_u64 v[104:105], v[104:105], 0, s[88:89]
	global_load_lds_dwordx4 v[106:107], off nt
	s_add_i32 m0, s6, 0xc000
	s_and_b32 s6, s8, 1
	global_load_lds_dwordx4 v[104:105], off nt
	s_mul_i32 s7, s6, 0xe000
	v_add_u32_e32 v160, s7, v101
	ds_read_b128 v[104:107], v160
	ds_read_b128 v[108:111], v160 offset:1024
	ds_read_b128 v[112:115], v160 offset:2048
	ds_read_b128 v[116:119], v160 offset:3072
	ds_read_b128 v[120:123], v160 offset:4096
	ds_read_b128 v[124:127], v160 offset:5120
	ds_read_b128 v[128:131], v160 offset:6144
	ds_read_b128 v[132:135], v160 offset:7168
	ds_read_b128 v[136:139], v160 offset:8192
	ds_read_b128 v[140:143], v160 offset:9216
	ds_read_b128 v[144:147], v160 offset:10240
	ds_read_b128 v[148:151], v160 offset:11264
	ds_read_b128 v[152:155], v160 offset:12288
	ds_read_b128 v[156:159], v160 offset:13312
	ds_read_b128 v[162:165], v160 offset:14336
	ds_read_b128 v[166:169], v160 offset:15360
	v_cvt_pk_bf16_f32 v175, v22, v23
	v_cvt_pk_bf16_f32 v176, v16, v17
	v_cvt_pk_bf16_f32 v177, v18, v19
	v_cvt_pk_bf16_f32 v178, v12, v13
	v_cvt_pk_bf16_f32 v179, v14, v15
	v_cvt_pk_bf16_f32 v180, v8, v9
	v_cvt_pk_bf16_f32 v181, v10, v11
	v_cvt_pk_bf16_f32 v196, v4, v5
	v_cvt_pk_bf16_f32 v197, v6, v7
	v_cvt_pk_bf16_f32 v198, v0, v1
	v_cvt_pk_bf16_f32 v199, v2, v3
	s_waitcnt lgkmcnt(0)
	v_mfma_f32_16x16x32_bf16 v[60:63], v[104:107], v[170:173], v[60:63]
	v_mfma_f32_16x16x32_bf16 v[56:59], v[120:123], v[170:173], v[56:59]
	v_mfma_f32_16x16x32_bf16 v[60:63], v[108:111], v[174:177], v[60:63]
	v_mfma_f32_16x16x32_bf16 v[56:59], v[124:127], v[174:177], v[56:59]
	v_mfma_f32_16x16x32_bf16 v[60:63], v[112:115], v[178:181], v[60:63]
	v_mfma_f32_16x16x32_bf16 v[56:59], v[128:131], v[178:181], v[56:59]
	v_mfma_f32_16x16x32_bf16 v[60:63], v[116:119], v[196:199], v[60:63]
	v_mfma_f32_16x16x32_bf16 v[56:59], v[132:135], v[196:199], v[56:59]
	ds_read_b128 v[104:107], v160 offset:16384
	ds_read_b128 v[108:111], v160 offset:17408
	ds_read_b128 v[112:115], v160 offset:18432
	ds_read_b128 v[116:119], v160 offset:19456
	ds_read_b128 v[120:123], v160 offset:20480
	ds_read_b128 v[124:127], v160 offset:21504
	ds_read_b128 v[128:131], v160 offset:22528
	ds_read_b128 v[132:135], v160 offset:23552
	v_mfma_f32_16x16x32_bf16 v[52:55], v[136:139], v[170:173], v[52:55]
	v_mfma_f32_16x16x32_bf16 v[48:51], v[152:155], v[170:173], v[48:51]
	v_mfma_f32_16x16x32_bf16 v[52:55], v[140:143], v[174:177], v[52:55]
	v_mfma_f32_16x16x32_bf16 v[48:51], v[156:159], v[174:177], v[48:51]
	v_mfma_f32_16x16x32_bf16 v[52:55], v[144:147], v[178:181], v[52:55]
	v_mfma_f32_16x16x32_bf16 v[48:51], v[162:165], v[178:181], v[48:51]
	v_mfma_f32_16x16x32_bf16 v[52:55], v[148:151], v[196:199], v[52:55]
	v_mfma_f32_16x16x32_bf16 v[48:51], v[166:169], v[196:199], v[48:51]
	ds_read_b128 v[136:139], v160 offset:24576
	ds_read_b128 v[140:143], v160 offset:25600
	ds_read_b128 v[144:147], v160 offset:26624
	ds_read_b128 v[148:151], v160 offset:27648
	ds_read_b128 v[152:155], v160 offset:28672
	ds_read_b128 v[156:159], v160 offset:29696
	ds_read_b128 v[162:165], v160 offset:30720
	ds_read_b128 v[166:169], v160 offset:31744
	s_waitcnt lgkmcnt(0)
; #define GD_LOAD8(dst, f0) do { _Pragma("unroll") for (int i_ = 0; i_ < 8; ++i_) dst[i_] = GD_FRAG((f0) + i_); } while (0)
; #define GD_PIN() __builtin_amdgcn_sched_barrier(0)
; __device__ __forceinline__ void gdn_scan_phase(const Frame& F0, const Args& a0, int nblk, bool last) {
;     ...
;         GD_PIN(); GD_LOAD8(fA, 24); GD_PIN();
; #pragma unroll
;         for (int i = 0; i < 8; ++i) O[i >> 2] = __builtin_amdgcn_mfma_f32_16x16x32_bf16(fC[i], Sf[i & 3], O[i >> 2], 0, 0, 0);
;         GD_PIN(); GD_LOAD8(fB, 32); GD_PIN();
; #pragma unroll
;         for (int i = 0; i < 8; ++i) O[2 + (i >> 2)] = __builtin_amdgcn_mfma_f32_16x16x32_bf16(fA[i], Sf[i & 3], O[2 + (i >> 2)], 0, 0, 0);
;         GD_PIN(); GD_LOAD8(fC, 40); GD_PIN();
;         bf16x8 Vf[2]; Vf[0] = pack8(V[0], V[1]); Vf[1] = pack8(V[2], V[3]);
; #pragma unroll
;         for (int t = 0; t < 8; ++t) S[t] = S[t] * gl;
; #pragma unroll
;         for (int i = 0; i < 8; ++i) S[i >> 1] = __builtin_amdgcn_mfma_f32_16x16x32_bf16(fB[i], Vf[i & 1], S[i >> 1], 0, 0, 0);
;         GD_PIN();
; #pragma unroll
;         for (int i_ = 0; i_ < 8; ++i_) if (i_ != 1 && i_ != 3) fA[i_] = GD_FRAG(48 + i_);
;         GD_PIN();
; #pragma unroll
;         for (int i = 0; i < 8; ++i) S[4 + (i >> 1)] = __builtin_amdgcn_mfma_f32_16x16x32_bf16(fC[i], Vf[i & 1], S[4 + (i >> 1)], 0, 0, 0);
; #pragma unroll
;         for (int i = 0; i < 8; ++i) if (i != 1 && i != 3) O[i >> 1] = __builtin_amdgcn_mfma_f32_16x16x32_bf16(fA[i], Vf[i & 1], O[i >> 1], 0, 0, 0);
;     ...
;         if (!(last && c < 4)) {
	v_mfma_f32_16x16x32_bf16 v[104:107], v[104:107], v[170:173], 0
	v_mfma_f32_16x16x32_bf16 v[104:107], v[108:111], v[174:177], v[104:107]
	v_mfma_f32_16x16x32_bf16 v[108:111], v[120:123], v[170:173], 0
	v_mfma_f32_16x16x32_bf16 v[108:111], v[124:127], v[174:177], v[108:111]
	v_mfma_f32_16x16x32_bf16 v[104:107], v[112:115], v[178:181], v[104:107]
	v_mfma_f32_16x16x32_bf16 v[108:111], v[128:131], v[178:181], v[108:111]
	v_mfma_f32_16x16x32_bf16 v[104:107], v[116:119], v[196:199], v[104:107]
	v_mfma_f32_16x16x32_bf16 v[108:111], v[132:135], v[196:199], v[108:111]
	ds_read_b128 v[112:115], v160 offset:32768
	ds_read_b128 v[116:119], v160 offset:33792
	ds_read_b128 v[120:123], v160 offset:34816
	ds_read_b128 v[124:127], v160 offset:35840
	ds_read_b128 v[128:131], v160 offset:36864
	ds_read_b128 v[132:135], v160 offset:37888
	ds_read_b128 v[200:203], v160 offset:38912
	ds_read_b128 v[204:207], v160 offset:39936
	v_mfma_f32_16x16x32_bf16 v[136:139], v[136:139], v[170:173], 0
	v_mfma_f32_16x16x32_bf16 v[136:139], v[140:143], v[174:177], v[136:139]
	v_mfma_f32_16x16x32_bf16 v[140:143], v[152:155], v[170:173], 0
	v_mfma_f32_16x16x32_bf16 v[140:143], v[156:159], v[174:177], v[140:143]
	v_mfma_f32_16x16x32_bf16 v[136:139], v[144:147], v[178:181], v[136:139]
	v_mfma_f32_16x16x32_bf16 v[140:143], v[162:165], v[178:181], v[140:143]
	v_mfma_f32_16x16x32_bf16 v[136:139], v[148:151], v[196:199], v[136:139]
	v_mfma_f32_16x16x32_bf16 v[140:143], v[166:169], v[196:199], v[140:143]
	ds_read_b128 v[144:147], v160 offset:40960
	ds_read_b128 v[148:151], v160 offset:41984
	ds_read_b128 v[152:155], v160 offset:43008
	ds_read_b128 v[156:159], v160 offset:44032
	ds_read_b128 v[162:165], v160 offset:45056
	ds_read_b128 v[166:169], v160 offset:46080
	ds_read_b128 v[170:173], v160 offset:47104
	ds_read_b128 v[174:177], v160 offset:48128
	v_cvt_pk_bf16_f32 v178, v60, v61
	v_cvt_pk_bf16_f32 v179, v62, v63
	v_cvt_pk_bf16_f32 v180, v56, v57
	v_cvt_pk_bf16_f32 v181, v58, v59
	v_pk_mul_f32 v[30:31], v[30:31], v[80:81] op_sel_hi:[1,0]
	v_pk_mul_f32 v[28:29], v[28:29], v[80:81] op_sel_hi:[1,0]
	v_pk_mul_f32 v[26:27], v[26:27], v[80:81] op_sel_hi:[1,0]
	v_pk_mul_f32 v[24:25], v[24:25], v[80:81] op_sel_hi:[1,0]
	v_pk_mul_f32 v[22:23], v[22:23], v[80:81] op_sel_hi:[1,0]
	v_pk_mul_f32 v[20:21], v[20:21], v[80:81] op_sel_hi:[1,0]
	v_pk_mul_f32 v[18:19], v[18:19], v[80:81] op_sel_hi:[1,0]
	v_pk_mul_f32 v[16:17], v[16:17], v[80:81] op_sel_hi:[1,0]
	s_waitcnt lgkmcnt(0)
	v_mfma_f32_16x16x32_bf16 v[28:31], v[112:115], v[178:181], v[28:31]
	v_cvt_pk_bf16_f32 v196, v52, v53
	v_cvt_pk_bf16_f32 v197, v54, v55
	v_cvt_pk_bf16_f32 v198, v48, v49
	v_mfma_f32_16x16x32_bf16 v[24:27], v[120:123], v[178:181], v[24:27]
	v_cvt_pk_bf16_f32 v199, v50, v51
	v_pk_mul_f32 v[14:15], v[14:15], v[80:81] op_sel_hi:[1,0]
	v_pk_mul_f32 v[12:13], v[12:13], v[80:81] op_sel_hi:[1,0]
	v_mfma_f32_16x16x32_bf16 v[20:23], v[128:131], v[178:181], v[20:23]
	v_mul_f32_e64 v10, v10, v80
	v_mul_f32_e64 v11, v11, v80
	v_pk_mul_f32 v[8:9], v[8:9], v[80:81] op_sel_hi:[1,0]
	v_pk_mul_f32 v[6:7], v[6:7], v[80:81] op_sel_hi:[1,0]
	v_mfma_f32_16x16x32_bf16 v[16:19], v[200:203], v[178:181], v[16:19]
	v_mul_f32_e64 v4, v4, v80
	v_mul_f32_e64 v5, v5, v80
	v_pk_mul_f32 v[2:3], v[2:3], v[80:81] op_sel_hi:[1,0]
	v_pk_mul_f32 v[0:1], v[0:1], v[80:81] op_sel_hi:[1,0]
	v_mfma_f32_16x16x32_bf16 v[28:31], v[116:119], v[196:199], v[28:31]
	v_mfma_f32_16x16x32_bf16 v[24:27], v[124:127], v[196:199], v[24:27]
	v_mfma_f32_16x16x32_bf16 v[20:23], v[132:135], v[196:199], v[20:23]
	v_mfma_f32_16x16x32_bf16 v[16:19], v[204:207], v[196:199], v[16:19]
	ds_read_b128 v[48:51], v160 offset:49152
	ds_read_b128 v[52:55], v160 offset:51200
	ds_read_b128 v[112:115], v160 offset:53248
	ds_read_b128 v[116:119], v160 offset:54272
	ds_read_b128 v[120:123], v160 offset:55296
	ds_read_b128 v[124:127], v160 offset:56320
	s_waitcnt lgkmcnt(0)
	v_mfma_f32_16x16x32_bf16 v[60:63], v[48:51], v[178:181], v[104:107]
	s_cmp_lt_i32 s27, 4
	s_cselect_b64 s[8:9], -1, 0
	s_and_b64 s[8:9], s[76:77], s[8:9]
	v_mfma_f32_16x16x32_bf16 v[48:51], v[112:115], v[178:181], v[136:139]
	s_and_b64 vcc, exec, s[8:9]
	v_mfma_f32_16x16x32_bf16 v[12:15], v[144:147], v[178:181], v[12:15]
	v_mfma_f32_16x16x32_bf16 v[8:11], v[152:155], v[178:181], v[8:11]
	v_mfma_f32_16x16x32_bf16 v[4:7], v[162:165], v[178:181], v[4:7]
	v_mfma_f32_16x16x32_bf16 v[0:3], v[170:173], v[178:181], v[0:3]
	v_mfma_f32_16x16x32_bf16 v[56:59], v[52:55], v[178:181], v[108:111]
	v_mfma_f32_16x16x32_bf16 v[52:55], v[116:119], v[196:199], v[48:51]
	v_mfma_f32_16x16x32_bf16 v[48:51], v[120:123], v[178:181], v[140:143]
	v_mfma_f32_16x16x32_bf16 v[12:15], v[148:151], v[196:199], v[12:15]
	v_mfma_f32_16x16x32_bf16 v[8:11], v[156:159], v[196:199], v[8:11]
	v_mfma_f32_16x16x32_bf16 v[4:7], v[166:169], v[196:199], v[4:7]
	v_mfma_f32_16x16x32_bf16 v[0:3], v[174:177], v[196:199], v[0:3]
	v_mfma_f32_16x16x32_bf16 v[48:51], v[124:127], v[196:199], v[48:51]
	s_cbranch_vccnz .LBB0_574
; #define LAS __attribute__((address_space(3)))
; __device__ __forceinline__ unsigned pk2(float lo, float hi) { return __builtin_bit_cast(unsigned, __builtin_convertvector((f32x2p){lo, hi}, bf16x2p)); }
; __device__ __forceinline__ void gdn_scan_phase(const Frame& F0, const Args& a0, int nblk, bool last) {
;     ...
;         if (!(last && c < 4)) {
;             LAS unsigned char* ob = ost + (s & 1) * 16384;
;             const bool ev = !(cc & 1);
; #pragma unroll
;             for (int mt = 0; mt < 4; ++mt) {
;                 const float s0 = ev ? O[mt][2] : O[mt][0], s1 = ev ? O[mt][3] : O[mt][1];
;                 const float r0 = __builtin_bit_cast(float, __builtin_amdgcn_mov_dpp(__builtin_bit_cast(int, s0), 0xB1, 0xF, 0xF, true));
;                 const float r1 = __builtin_bit_cast(float, __builtin_amdgcn_mov_dpp(__builtin_bit_cast(int, s1), 0xB1, 0xF, 0xF, true));
;                 const unsigned w0 = ev ? pk2(O[mt][0], r0) : pk2(r0, O[mt][2]), w1 = ev ? pk2(O[mt][1], r1) : pk2(r1, O[mt][3]);
; #pragma unroll
;                 for (int e = 0; e < 2; ++e) { const int p = 16 * mt + 4 * g + (ev ? 0 : 2) + e, tok = d ? 63 - p : p;
;                     *(LAS unsigned*)(ob + tok * 256 + (((2 * n + (cc >> 3)) ^ (((tok >> 2) & 3) << 2)) * 16) + (cc & 6) * 2) = e ? w1 : w0; } }
;         }
	s_lshl_b32 s6, s6, 14
	s_add_i32 s6, s6, 0
	v_cmp_eq_u32_e32 vcc, 1, v68
	s_add_i32 s36, s6, 0x1c000
	v_cmp_eq_u32_e64 s[6:7], 2, v68
	v_cndmask_b32_e32 v80, v60, v61, vcc
	v_cmp_eq_u32_e64 s[8:9], 3, v68
	v_cndmask_b32_e64 v80, v80, v62, s[6:7]
	v_cmp_eq_u32_e64 s[10:11], 1, v66
	v_cndmask_b32_e64 v80, v80, v63, s[8:9]
	v_cmp_eq_u32_e64 s[14:15], 2, v66
	v_cndmask_b32_e64 v104, v60, v61, s[10:11]
	v_mov_b32_dpp v80, v80 quad_perm:[1,0,3,2] row_mask:0xf bank_mask:0xf bound_ctrl:1
	v_cndmask_b32_e64 v104, v104, v62, s[14:15]
	v_cmp_eq_u32_e64 s[16:17], 3, v66
	v_cndmask_b32_e64 v60, v80, v60, s[2:3]
	v_cndmask_b32_e64 v62, v62, v80, s[2:3]
	v_cndmask_b32_e64 v104, v104, v63, s[16:17]
	v_cvt_pk_bf16_f32 v60, v60, v62
	v_add_u32_e32 v62, s36, v97
	v_mov_b32_dpp v104, v104 quad_perm:[1,0,3,2] row_mask:0xf bank_mask:0xf bound_ctrl:1
	v_cndmask_b32_e64 v61, v104, v61, s[2:3]
	v_cndmask_b32_e64 v63, v63, v104, s[2:3]
	v_add3_u32 v62, v62, v98, v84
	ds_write_b32 v62, v60
	v_cvt_pk_bf16_f32 v60, v61, v63
	v_add_u32_e32 v61, s36, v99
	v_add3_u32 v61, v61, v100, v84
	ds_write_b32 v61, v60
	v_cndmask_b32_e32 v60, v56, v57, vcc
	v_cndmask_b32_e64 v60, v60, v58, s[6:7]
	v_cndmask_b32_e64 v60, v60, v59, s[8:9]
	v_cndmask_b32_e64 v61, v56, v57, s[10:11]
	v_cndmask_b32_e64 v61, v61, v58, s[14:15]
	v_mov_b32_dpp v60, v60 quad_perm:[1,0,3,2] row_mask:0xf bank_mask:0xf bound_ctrl:1
	v_cndmask_b32_e64 v61, v61, v59, s[16:17]
	v_cndmask_b32_e64 v56, v60, v56, s[2:3]
	v_cndmask_b32_e64 v58, v58, v60, s[2:3]
	v_mov_b32_dpp v61, v61 quad_perm:[1,0,3,2] row_mask:0xf bank_mask:0xf bound_ctrl:1
	v_cvt_pk_bf16_f32 v56, v56, v58
	v_add_u32_e32 v58, s36, v93
	v_cndmask_b32_e64 v57, v61, v57, s[2:3]
	v_cndmask_b32_e64 v59, v59, v61, s[2:3]
	v_add3_u32 v58, v58, v94, v84
	ds_write_b32 v58, v56
	v_cvt_pk_bf16_f32 v56, v57, v59
	v_add_u32_e32 v57, s36, v95
	v_add3_u32 v57, v57, v96, v84
	ds_write_b32 v57, v56
	v_cndmask_b32_e32 v56, v52, v53, vcc
	v_cndmask_b32_e64 v56, v56, v54, s[6:7]
	v_cndmask_b32_e64 v56, v56, v55, s[8:9]
	v_cndmask_b32_e64 v57, v52, v53, s[10:11]
	v_cndmask_b32_e64 v57, v57, v54, s[14:15]
	v_mov_b32_dpp v56, v56 quad_perm:[1,0,3,2] row_mask:0xf bank_mask:0xf bound_ctrl:1
	v_cndmask_b32_e64 v57, v57, v55, s[16:17]
	v_cndmask_b32_e64 v52, v56, v52, s[2:3]
	v_cndmask_b32_e64 v54, v54, v56, s[2:3]
	v_mov_b32_dpp v57, v57 quad_perm:[1,0,3,2] row_mask:0xf bank_mask:0xf bound_ctrl:1
	v_cvt_pk_bf16_f32 v52, v52, v54
	v_add_u32_e32 v54, s36, v89
	v_cndmask_b32_e64 v53, v57, v53, s[2:3]
	v_cndmask_b32_e64 v55, v55, v57, s[2:3]
	v_add3_u32 v54, v54, v90, v84
	ds_write_b32 v54, v52
	v_cvt_pk_bf16_f32 v52, v53, v55
	v_add_u32_e32 v53, s36, v91
	v_add3_u32 v53, v53, v92, v84
	ds_write_b32 v53, v52
	v_cndmask_b32_e32 v52, v48, v49, vcc
	v_cndmask_b32_e64 v52, v52, v50, s[6:7]
	v_cndmask_b32_e64 v52, v52, v51, s[8:9]
	v_cndmask_b32_e64 v53, v48, v49, s[10:11]
	v_cndmask_b32_e64 v53, v53, v50, s[14:15]
	v_mov_b32_dpp v52, v52 quad_perm:[1,0,3,2] row_mask:0xf bank_mask:0xf bound_ctrl:1
	v_cndmask_b32_e64 v53, v53, v51, s[16:17]
	v_cndmask_b32_e64 v48, v52, v48, s[2:3]
	v_cndmask_b32_e64 v50, v50, v52, s[2:3]
	v_mov_b32_dpp v53, v53 quad_perm:[1,0,3,2] row_mask:0xf bank_mask:0xf bound_ctrl:1
	v_cvt_pk_bf16_f32 v48, v48, v50
	v_add_u32_e32 v50, s36, v85
	v_cndmask_b32_e64 v49, v53, v49, s[2:3]
	v_cndmask_b32_e64 v51, v51, v53, s[2:3]
	v_add3_u32 v50, v50, v86, v84
	ds_write_b32 v50, v48
	v_cvt_pk_bf16_f32 v48, v49, v51
	v_add_u32_e32 v49, s36, v87
	v_add3_u32 v49, v49, v88, v84
	ds_write_b32 v49, v48
